# diff job prologue: second key stage's loads issued right behind the first stage's (plus the late bias-table write); counted waits adjusted
# speedup vs baseline: 1.0011x; 1.0003x over previous
; DI int swap23(int k) { return (k & ~12) | ((k & 4) << 1) | ((k & 8) >> 1); }
; DI void diff_job8(const Params& p, int layer, int b, int head, int qb, unsigned char* smem) {
;   int tid_ = threadIdx.x; asm volatile("" : "+v"(tid_));
;   const int tid = tid_, lane = tid & 63, wave = tid >> 6, h = lane >> 5, lq = lane & 31;
;   const int map = wave >> 2, qg = wave & 3;
;   const int t0 = qb * 128, tw0 = t0 + 32 * qg, tq = tw0 + lq;
;   const float* lut = (const float*)(smem + LUT_OFF);
;   build_lut(p, 4 + head, smem, tid);
;   bf16x8 qf[4];
;   {
;     const u16* qr = p.qdf + (size_t)(b * TP + tq) * 512 + head * 128 + 64 * map + 8 * h;
; #pragma unroll
;     for (int s = 0; s < 4; ++s) qf[s] = *(const bf16x8*)(qr + 16 * s);
;   }
;   f32x16 O[4];
; #pragma unroll
;   for (int i = 0; i < 4; ++i) O[i] = zero16();
;   float m = -1e30f, l = 0.f;
;   const u16* K1 = p.kdf + (size_t)b * TP * 512 + head * 128;
;   const u16* VT = p.vtdf + (size_t)(b * 512 + head * 128) * TP;
;   const int ntile = 2 * (qb + 1);
;   const int krow = tid >> 3, kc = tid & 7, krs = swap23(krow);
;   u32x4 rk1, rk2, rv[2];
;   auto gl = [&](int k0) {
;     const u16* s = K1 + (size_t)(k0 + krow) * 512 + kc * 8;
;     rk1 = *(const u32x4*)s; rk2 = *(const u32x4*)(s + 64);
; #pragma unroll
;     for (int i = 0; i < 2; ++i) rv[i] = *(const u32x4*)(VT + (size_t)(krow + 64 * i) * TP + k0 + kc * 8);
;   };
;   auto sl = [&](unsigned char* d) {
;     *(u32x4*)(d + krs * 144 + kc * 16) = rk1;
;     *(u32x4*)(d + 9216 + krs * 144 + kc * 16) = rk2;
; #pragma unroll
;     for (int i = 0; i < 2; ++i) *(u32x4*)(d + 18432 + (krow + 64 * i) * 144 + kc * 16) = rv[i];
;   };
;   gl(0); sl(smem);
;   if (ntile > 1) gl(64);
;   __syncthreads();
;   const float cbias = lut[128];
.LBB0_918:
	s_or_b64 exec, exec, s[2:3]
	s_ashr_i32 s2, s10, 31
	s_lshr_b32 s2, s2, 27
	s_add_i32 s2, s10, s2
	s_ashr_i32 s2, s2, 5
	v_lshrrev_b32_e32 v0, 1, v150
	s_load_dwordx16 s[56:71], s[0:1], 0x108
	s_sub_i32 s7, 32, s2
	v_and_b32_e32 v149, 0x60, v0
	s_bfe_u32 s4, s10, 0x30002
	v_and_b32_e32 v148, 31, v150
	v_lshl_or_b32 v152, s7, 7, v149
	v_or_b32_e32 v153, v152, v148
	s_mul_i32 s2, s4, 0x1080
	v_add_u32_e32 v0, s2, v153
	s_lshl_b32 s31, s6, 7
	s_lshl_b32 s10, s6, 8
	s_mul_i32 s2, s4, 0x420000
	v_ashrrev_i32_e32 v131, 8, v150
	v_lshlrev_b64 v[2:3], 10, v[0:1]
	s_waitcnt lgkmcnt(0)
	s_add_u32 s2, s58, s2
	v_lshl_add_u64 v[2:3], s[56:57], 0, v[2:3]
	v_lshlrev_b32_e32 v4, 6, v131
	s_addc_u32 s3, s59, 0
	v_bfe_u32 v6, v150, 5, 1
	v_lshl_add_u64 v[2:3], v[2:3], 0, s[10:11]
	v_ashrrev_i32_e32 v5, 31, v4
	s_add_u32 s2, s2, s10
	v_lshlrev_b64 v[132:133], 9, v[0:1]
	v_lshl_add_u64 v[2:3], v[4:5], 1, v[2:3]
	v_lshlrev_b32_e32 v0, 4, v6
	s_addc_u32 s3, s3, 0
	s_lshl_b32 s4, s4, 9
	v_lshl_add_u64 v[2:3], v[2:3], 0, v[0:1]
	s_or_b32 s4, s4, s31
	v_ashrrev_i32_e32 v134, 3, v150
	global_load_dwordx4 v[98:101], v[2:3], off
	global_load_dwordx4 v[102:105], v[2:3], off offset:32
	global_load_dwordx4 v[106:109], v[2:3], off offset:64
	global_load_dwordx4 v[110:113], v[2:3], off offset:96
	s_mulk_i32 s4, 0x2100
	v_lshlrev_b32_e32 v3, 1, v134
	v_lshrrev_b32_e32 v4, 1, v134
	s_add_u32 s4, s64, s4
	v_and_b32_e32 v2, 0xffffff3, v134
	v_and_b32_e32 v3, 8, v3
	v_and_b32_e32 v4, 4, v4
	v_ashrrev_i32_e32 v135, 31, v134
	s_addc_u32 s5, s65, 0
	v_or3_b32 v20, v3, v2, v4
	v_lshlrev_b64 v[2:3], 10, v[134:135]
	v_lshlrev_b32_e32 v4, 4, v150
	v_lshl_add_u64 v[2:3], s[2:3], 0, v[2:3]
	v_and_b32_e32 v136, 0x70, v4
	v_mov_b32_e32 v137, v1
	v_mov_b64_e32 v[14:15], s[4:5]
	s_movk_i32 s6, 0x2100
	v_lshlrev_b32_e32 v130, 3, v6
	v_lshl_add_u64 v[6:7], v[2:3], 0, v[136:137]
	v_mad_i64_i32 v[10:11], s[4:5], v134, s6, v[14:15]
	v_add_u32_e32 v18, 64, v134
	global_load_dwordx4 v[2:5], v[6:7], off
	s_nop 0
	global_load_dwordx4 v[6:9], v[6:7], off offset:128
	v_lshl_add_u64 v[138:139], v[10:11], 0, v[136:137]
	v_mad_i64_i32 v[14:15], s[4:5], v18, s6, v[14:15]
	global_load_dwordx4 v[10:13], v[138:139], off
	v_lshl_add_u64 v[140:141], v[14:15], 0, v[136:137]
	global_load_dwordx4 v[14:17], v[140:141], off
	v_mul_lo_u32 v135, v20, s78
	v_add_u32_e32 v20, v135, v136
	v_mul_lo_u32 v154, v134, s78
	v_ashrrev_i32_e32 v19, 31, v18
	v_lshlrev_b64 v[18:19], 10, v[18:19]
	v_lshl_add_u64 v[18:19], s[2:3], 0, v[18:19]
	v_lshl_add_u64 v[18:19], v[18:19], 0, v[136:137]
	global_load_dwordx4 v[114:117], v[18:19], off
	global_load_dwordx4 v[118:121], v[18:19], off offset:128
	global_load_dwordx4 v[122:125], v[138:139], off offset:128
	global_load_dwordx4 v[126:129], v[140:141], off offset:128
	v_mov_b32_e32 v50, v1
	v_mov_b32_e32 v51, v1
	s_lshl_b32 s10, s7, 1
	v_mov_b32_e32 v52, v1
	v_mov_b32_e32 v53, v1
	v_mov_b32_e32 v54, v1
	v_mov_b32_e32 v55, v1
	v_mov_b32_e32 v56, v1
	v_mov_b32_e32 v57, v1
	v_mov_b32_e32 v58, v1
	v_mov_b32_e32 v59, v1
	v_mov_b32_e32 v60, v1
	v_mov_b32_e32 v61, v1
	v_mov_b32_e32 v62, v1
	v_mov_b32_e32 v63, v1
	s_waitcnt vmcnt(19)
	v_mov_b32_e32 v64, v1
	v_mov_b32_e32 v65, v1
	s_waitcnt vmcnt(12)
	v_cmp_gt_i32_e32 vcc, 0x81, v150
	s_and_saveexec_b64 s[8:9], vcc
	v_mul_f32_e32 v255, 0x3fb8aa3b, v255
	ds_write_b32 v254, v255
	s_or_b64 exec, exec, s[8:9]
	v_mov_b64_e32 v[34:35], v[50:51]
	v_and_b32_e32 v151, 63, v150
	s_add_i32 s42, s10, 2
	v_lshl_add_u64 v[142:143], s[2:3], 0, v[136:137]
	v_subrev_u32_e32 v156, 63, v152
	v_add_u32_e32 v157, 0xffffff90, v152
	v_or_b32_e32 v158, 31, v152
	v_mul_u32_u24_e32 v159, 0x90, v148
	v_mov_b32_e32 v161, 0xf149f2ca
	v_mov_b32_e32 v160, 0
	v_mov_b64_e32 v[36:37], v[52:53]
	v_mov_b64_e32 v[38:39], v[54:55]
	s_waitcnt vmcnt(7)
	ds_write_b128 v20, v[2:5]
	s_waitcnt vmcnt(6)
	ds_write_b128 v20, v[6:9] offset:9216
	v_add_u32_e32 v2, v154, v136
	s_waitcnt vmcnt(5)
	ds_write_b128 v2, v[10:13] offset:18432
	s_waitcnt vmcnt(4)
	ds_write_b128 v2, v[14:17] offset:27648
	v_add_u32_e32 v2, -4, v213
	v_mov_b32_e32 v3, 0xff800000
	ds_write_b32 v2, v3
	s_waitcnt lgkmcnt(0)
	s_barrier
	ds_read_b32 v155, v204
	v_mov_b64_e32 v[2:3], v[50:51]
	v_mov_b64_e32 v[18:19], v[50:51]
	v_mul_i32_i24_e32 v137, 0x2400, v131
	s_mov_b32 s2, 0
	v_mov_b64_e32 v[4:5], v[52:53]
	v_mov_b64_e32 v[6:7], v[54:55]
	v_mov_b64_e32 v[8:9], v[56:57]
	v_mov_b64_e32 v[10:11], v[58:59]
	v_mov_b64_e32 v[12:13], v[60:61]
	v_mov_b64_e32 v[14:15], v[62:63]
	v_mov_b64_e32 v[16:17], v[64:65]
	v_mov_b64_e32 v[20:21], v[52:53]
	v_mov_b64_e32 v[22:23], v[54:55]
	v_mov_b64_e32 v[24:25], v[56:57]
	v_mov_b64_e32 v[26:27], v[58:59]
	v_mov_b64_e32 v[28:29], v[60:61]
	v_mov_b64_e32 v[30:31], v[62:63]
	v_mov_b64_e32 v[32:33], v[64:65]
	v_mov_b64_e32 v[40:41], v[56:57]
	v_mov_b64_e32 v[42:43], v[58:59]
	v_mov_b64_e32 v[44:45], v[60:61]
	v_mov_b64_e32 v[46:47], v[62:63]
	v_mov_b64_e32 v[48:49], v[64:65]
